# gemm2 K loop: the register-staged tile of the second half gets its own registers (v220-v251) and its global loads move from the end to the top of the first half (two K tiles of latency cover instead o
# baseline (speedup 1.0000x reference)
; DI void gemm_kloop(const bf16_t* __restrict__ A, int lda, const bf16_t* __restrict__ B, int ldb, int K, bf16_t* sm,
;                    f32x4 (&acc)[4][4]) {
;     ...
;   __syncthreads();
;   GLOAD(ra0, rb0, 0)
;   GLOAD(ra1, rb1, 64)
;   SSTORE(ra0, rb0, 0)
;   __syncthreads();
;   for (int kt = 0; kt < nk - 2; kt += 2) {
;     GLOAD(ra0, rb0, (kt + 2) << 6)
;     COMPUTE(0)
;     SSTORE(ra1, rb1, 1)
;     __syncthreads();
.LBB0_1701:
	ds_read_b128 v[110:113], v102
	ds_read_b128 v[114:117], v103 offset:18432
	ds_read_b128 v[118:121], v102 offset:64
	ds_read_b128 v[122:125], v103 offset:18496
	ds_read_b128 v[126:129], v103 offset:20736
	ds_read_b128 v[130:133], v103 offset:20800
	ds_read_b128 v[134:137], v103 offset:23040
	ds_read_b128 v[138:141], v103 offset:23104
	ds_read_b128 v[142:145], v103 offset:25344
	ds_read_b128 v[146:149], v103 offset:25408
	s_waitcnt lgkmcnt(8)
	v_mfma_f32_16x16x32_bf16 v[96:99], v[110:113], v[114:117], v[96:99]
	v_lshl_add_u64 v[162:163], s[10:11], 0, v[104:105]
	v_lshl_add_u64 v[176:177], s[12:13], 0, v[104:105]
	global_load_dwordx4 v[224:227], v[176:177], off offset:256
	global_load_dwordx4 v[220:223], v[162:163], off offset:256
	v_add_co_u32_e32 v178, vcc, s85, v162
	s_waitcnt lgkmcnt(5)
	v_mfma_f32_16x16x32_bf16 v[88:91], v[110:113], v[126:129], v[88:91]
	v_addc_co_u32_e32 v179, vcc, 0, v163, vcc
	global_load_dwordx4 v[228:231], v[178:179], off offset:256
	v_add_co_u32_e32 v180, vcc, s88, v162
	s_waitcnt lgkmcnt(3)
	v_mfma_f32_16x16x32_bf16 v[84:87], v[110:113], v[134:137], v[84:87]
	v_addc_co_u32_e32 v181, vcc, 0, v163, vcc
	global_load_dwordx4 v[232:235], v[180:181], off offset:256
	v_add_co_u32_e32 v208, vcc, s89, v162
	s_waitcnt lgkmcnt(1)
	v_mfma_f32_16x16x32_bf16 v[80:83], v[110:113], v[142:145], v[80:83]
	ds_read_b128 v[110:113], v102 offset:2304
	ds_read_b128 v[150:153], v102 offset:2368
	v_addc_co_u32_e32 v209, vcc, 0, v163, vcc
	global_load_dwordx4 v[236:239], v[208:209], off offset:256
	s_waitcnt lgkmcnt(1)
	v_mfma_f32_16x16x32_bf16 v[76:79], v[110:113], v[114:117], v[76:79]
	v_add_co_u32_e32 v210, vcc, s85, v176
	s_add_i32 s9, s9, 2
	v_mfma_f32_16x16x32_bf16 v[72:75], v[110:113], v[126:129], v[72:75]
	v_addc_co_u32_e32 v211, vcc, 0, v177, vcc
	global_load_dwordx4 v[240:243], v[210:211], off offset:256
	v_add_co_u32_e32 v212, vcc, s88, v176
	v_mfma_f32_16x16x32_bf16 v[68:71], v[110:113], v[134:137], v[68:71]
	s_nop 0
	v_addc_co_u32_e32 v213, vcc, 0, v177, vcc
	global_load_dwordx4 v[244:247], v[212:213], off offset:256
	v_add_co_u32_e32 v214, vcc, s89, v176
	v_mfma_f32_16x16x32_bf16 v[64:67], v[110:113], v[142:145], v[64:67]
	ds_read_b128 v[110:113], v102 offset:4608
	ds_read_b128 v[154:157], v102 offset:4672
	v_addc_co_u32_e32 v215, vcc, 0, v177, vcc
	global_load_dwordx4 v[248:251], v[214:215], off offset:256
	s_waitcnt lgkmcnt(1)
	v_mfma_f32_16x16x32_bf16 v[60:63], v[110:113], v[114:117], v[60:63]
	s_add_u32 s12, s12, 0x100
	s_addc_u32 s13, s13, 0
	s_add_u32 s10, s10, 0x100
	v_mfma_f32_16x16x32_bf16 v[56:59], v[110:113], v[126:129], v[56:59]
	s_addc_u32 s11, s11, 0
	s_cmp_lt_u32 s9, 12
	v_mfma_f32_16x16x32_bf16 v[52:55], v[110:113], v[134:137], v[52:55]
	v_mfma_f32_16x16x32_bf16 v[48:51], v[110:113], v[142:145], v[48:51]
	ds_read_b128 v[110:113], v102 offset:6912
	ds_read_b128 v[158:161], v102 offset:6976
	s_waitcnt vmcnt(15)
	ds_write_b128 v107, v[4:7] offset:36864
	s_waitcnt vmcnt(14)
	ds_write_b128 v107, v[24:27] offset:41472
	s_waitcnt vmcnt(13)
	ds_write_b128 v107, v[8:11] offset:46080
	s_waitcnt vmcnt(12)
	ds_write_b128 v107, v[12:15] offset:50688
	s_waitcnt vmcnt(11)
	ds_write_b128 v107, v[28:31] offset:55296
	s_waitcnt lgkmcnt(6)
	v_mfma_f32_16x16x32_bf16 v[44:47], v[110:113], v[114:117], v[44:47]
	s_waitcnt vmcnt(10)
	ds_write_b128 v107, v[16:19] offset:59904
	s_waitcnt vmcnt(9)
	ds_write_b128 v107, v[20:23] offset:64512
	s_waitcnt vmcnt(8)
	ds_write_b128 v108, v[32:35] offset:32256
	v_mfma_f32_16x16x32_bf16 v[40:43], v[110:113], v[126:129], v[40:43]
	v_mfma_f32_16x16x32_bf16 v[92:95], v[110:113], v[134:137], v[92:95]
	v_mfma_f32_16x16x32_bf16 v[36:39], v[110:113], v[142:145], v[36:39]
	v_mfma_f32_16x16x32_bf16 v[96:99], v[118:121], v[122:125], v[96:99]
	v_mfma_f32_16x16x32_bf16 v[88:91], v[118:121], v[130:133], v[88:91]
	v_mfma_f32_16x16x32_bf16 v[4:7], v[118:121], v[138:141], v[84:87]
	v_mfma_f32_16x16x32_bf16 v[8:11], v[118:121], v[146:149], v[80:83]
	v_mfma_f32_16x16x32_bf16 v[12:15], v[150:153], v[122:125], v[76:79]
	v_mfma_f32_16x16x32_bf16 v[16:19], v[150:153], v[130:133], v[72:75]
	v_mfma_f32_16x16x32_bf16 v[20:23], v[150:153], v[138:141], v[68:71]
	v_mfma_f32_16x16x32_bf16 v[24:27], v[150:153], v[146:149], v[64:67]
	v_mfma_f32_16x16x32_bf16 v[28:31], v[154:157], v[122:125], v[60:63]
	s_waitcnt lgkmcnt(8)
	v_mfma_f32_16x16x32_bf16 v[44:47], v[158:161], v[122:125], v[44:47]
	s_waitcnt lgkmcnt(0)
	s_barrier
; DI void gemm_kloop(const bf16_t* __restrict__ A, int lda, const bf16_t* __restrict__ B, int ldb, int K, bf16_t* sm,
;                    f32x4 (&acc)[4][4]) {
;     ...
;     GLOAD(ra1, rb1, (kt + 3) << 6)
;     COMPUTE(1)
;     SSTORE(ra0, rb0, 0)
;     __syncthreads();
;   }
	ds_read_b128 v[60:63], v102 offset:36864
	v_mfma_f32_16x16x32_bf16 v[32:35], v[154:157], v[130:133], v[56:59]
	v_mfma_f32_16x16x32_bf16 v[40:43], v[158:161], v[130:133], v[40:43]
	v_mfma_f32_16x16x32_bf16 v[56:59], v[158:161], v[138:141], v[92:95]
	ds_read_b128 v[64:67], v103 offset:55296
	ds_read_b128 v[68:71], v102 offset:36928
	s_nop 0
	ds_read_b128 v[92:95], v103 offset:55360
	ds_read_b128 v[76:79], v103 offset:57600
	ds_read_b128 v[130:133], v103 offset:57664
	v_mfma_f32_16x16x32_bf16 v[52:55], v[154:157], v[138:141], v[52:55]
	ds_read_b128 v[84:87], v103 offset:59904
	ds_read_b128 v[138:141], v103 offset:59968
	v_mfma_f32_16x16x32_bf16 v[48:51], v[154:157], v[146:149], v[48:51]
	v_mfma_f32_16x16x32_bf16 v[36:39], v[158:161], v[146:149], v[36:39]
	s_waitcnt lgkmcnt(3)
	v_mfma_f32_16x16x32_bf16 v[80:83], v[60:63], v[76:79], v[88:91]
	s_nop 2
	ds_read_b128 v[88:91], v103 offset:62208
	ds_read_b128 v[146:149], v103 offset:62272
	v_mfma_f32_16x16x32_bf16 v[72:75], v[60:63], v[64:67], v[96:99]
	s_waitcnt lgkmcnt(3)
	v_mfma_f32_16x16x32_bf16 v[4:7], v[60:63], v[84:87], v[4:7]
	s_waitcnt lgkmcnt(1)
	v_mfma_f32_16x16x32_bf16 v[8:11], v[60:63], v[88:91], v[8:11]
	ds_read_b128 v[60:63], v102 offset:39168
	ds_read_b128 v[154:157], v102 offset:39232
	s_waitcnt lgkmcnt(1)
	v_mfma_f32_16x16x32_bf16 v[12:15], v[60:63], v[64:67], v[12:15]
	v_mfma_f32_16x16x32_bf16 v[16:19], v[60:63], v[76:79], v[16:19]
	v_mfma_f32_16x16x32_bf16 v[20:23], v[60:63], v[84:87], v[20:23]
	v_mfma_f32_16x16x32_bf16 v[24:27], v[60:63], v[88:91], v[24:27]
	ds_read_b128 v[60:63], v102 offset:41472
	ds_read_b128 v[158:161], v102 offset:41536
	s_waitcnt lgkmcnt(1)
	v_mfma_f32_16x16x32_bf16 v[28:31], v[60:63], v[64:67], v[28:31]
	v_mfma_f32_16x16x32_bf16 v[32:35], v[60:63], v[76:79], v[32:35]
	v_mfma_f32_16x16x32_bf16 v[52:55], v[60:63], v[84:87], v[52:55]
	v_mfma_f32_16x16x32_bf16 v[48:51], v[60:63], v[88:91], v[48:51]
	ds_read_b128 v[60:63], v102 offset:43776
	ds_read_b128 v[168:171], v102 offset:43840
	s_waitcnt lgkmcnt(1)
	v_mfma_f32_16x16x32_bf16 v[44:47], v[60:63], v[64:67], v[44:47]
	v_mfma_f32_16x16x32_bf16 v[40:43], v[60:63], v[76:79], v[40:43]
	v_mfma_f32_16x16x32_bf16 v[172:175], v[60:63], v[84:87], v[56:59]
	v_mfma_f32_16x16x32_bf16 v[36:39], v[60:63], v[88:91], v[36:39]
	v_mfma_f32_16x16x32_bf16 v[96:99], v[68:71], v[92:95], v[72:75]
	v_mfma_f32_16x16x32_bf16 v[88:91], v[68:71], v[130:133], v[80:83]
	v_mfma_f32_16x16x32_bf16 v[84:87], v[68:71], v[138:141], v[4:7]
	v_mfma_f32_16x16x32_bf16 v[80:83], v[68:71], v[146:149], v[8:11]
	s_nop 1
	global_load_dwordx4 v[4:7], v[162:163], off offset:384
	v_mfma_f32_16x16x32_bf16 v[76:79], v[154:157], v[92:95], v[12:15]
	v_mfma_f32_16x16x32_bf16 v[72:75], v[154:157], v[130:133], v[16:19]
	v_mfma_f32_16x16x32_bf16 v[68:71], v[154:157], v[138:141], v[20:23]
	v_mfma_f32_16x16x32_bf16 v[64:67], v[154:157], v[146:149], v[24:27]
	s_nop 2
	global_load_dwordx4 v[24:27], v[178:179], off offset:384
	global_load_dwordx4 v[8:11], v[180:181], off offset:384
	global_load_dwordx4 v[12:15], v[208:209], off offset:384
	v_mfma_f32_16x16x32_bf16 v[60:63], v[158:161], v[92:95], v[28:31]
	s_nop 2
	global_load_dwordx4 v[28:31], v[176:177], off offset:384
	global_load_dwordx4 v[16:19], v[210:211], off offset:384
	global_load_dwordx4 v[20:23], v[212:213], off offset:384
	v_mfma_f32_16x16x32_bf16 v[56:59], v[158:161], v[130:133], v[32:35]
	s_nop 2
	global_load_dwordx4 v[32:35], v[214:215], off offset:384
	v_mfma_f32_16x16x32_bf16 v[52:55], v[158:161], v[138:141], v[52:55]
	s_waitcnt vmcnt(14)
	ds_write_b128 v107, v[220:223]
	ds_write_b128 v107, v[224:227] offset:18432
	s_waitcnt vmcnt(13)
	ds_write_b128 v107, v[228:231] offset:4608
	s_waitcnt vmcnt(12)
	ds_write_b128 v107, v[232:235] offset:9216
	s_waitcnt vmcnt(11)
	ds_write_b128 v107, v[236:239] offset:13824
	s_waitcnt vmcnt(10)
	ds_write_b128 v107, v[240:243] offset:23040
	s_waitcnt vmcnt(9)
	ds_write_b128 v107, v[244:247] offset:27648
	s_waitcnt vmcnt(8)
	ds_write_b128 v107, v[248:251] offset:32256
	s_waitcnt lgkmcnt(0)
	s_barrier
	v_mfma_f32_16x16x32_bf16 v[48:51], v[158:161], v[146:149], v[48:51]
	v_mfma_f32_16x16x32_bf16 v[44:47], v[168:171], v[92:95], v[44:47]
	v_mfma_f32_16x16x32_bf16 v[40:43], v[168:171], v[130:133], v[40:43]
	v_mfma_f32_16x16x32_bf16 v[92:95], v[168:171], v[138:141], v[172:175]
	v_mfma_f32_16x16x32_bf16 v[36:39], v[168:171], v[146:149], v[36:39]
	s_cbranch_scc1 .LBB0_1701
; DI void gemm_kloop(const bf16_t* __restrict__ A, int lda, const bf16_t* __restrict__ B, int ldb, int K, bf16_t* sm,
;                    f32x4 (&acc)[4][4]) {
;     ...
;   COMPUTE(0)
;   SSTORE(ra1, rb1, 1)
;   __syncthreads();
;   COMPUTE(1)
;   __syncthreads();
	ds_read_b128 v[110:113], v102
	ds_read_b128 v[114:117], v103 offset:18432
	ds_read_b128 v[118:121], v103 offset:20736
	ds_read_b128 v[122:125], v103 offset:23040
	ds_read_b128 v[126:129], v103 offset:25344
	s_movk_i32 s9, 0x5ff
	s_waitcnt lgkmcnt(3)
	v_mfma_f32_16x16x32_bf16 v[96:99], v[110:113], v[114:117], v[96:99]
	s_waitcnt lgkmcnt(2)
	v_mfma_f32_16x16x32_bf16 v[88:91], v[110:113], v[118:121], v[88:91]
	s_waitcnt lgkmcnt(1)
	v_mfma_f32_16x16x32_bf16 v[84:87], v[110:113], v[122:125], v[84:87]
	s_waitcnt lgkmcnt(0)
	v_mfma_f32_16x16x32_bf16 v[80:83], v[110:113], v[126:129], v[80:83]
	ds_read_b128 v[110:113], v102 offset:2304
	s_waitcnt lgkmcnt(0)
	v_mfma_f32_16x16x32_bf16 v[76:79], v[110:113], v[114:117], v[76:79]
	v_mfma_f32_16x16x32_bf16 v[72:75], v[110:113], v[118:121], v[72:75]
	v_mfma_f32_16x16x32_bf16 v[68:71], v[110:113], v[122:125], v[68:71]
	v_mfma_f32_16x16x32_bf16 v[64:67], v[110:113], v[126:129], v[64:67]
	ds_read_b128 v[110:113], v102 offset:4608
	s_waitcnt lgkmcnt(0)
	v_mfma_f32_16x16x32_bf16 v[60:63], v[110:113], v[114:117], v[60:63]
	v_mfma_f32_16x16x32_bf16 v[56:59], v[110:113], v[118:121], v[56:59]
	v_mfma_f32_16x16x32_bf16 v[52:55], v[110:113], v[122:125], v[52:55]
	v_mfma_f32_16x16x32_bf16 v[48:51], v[110:113], v[126:129], v[48:51]
	ds_read_b128 v[110:113], v102 offset:6912
	s_waitcnt lgkmcnt(0)
	v_mfma_f32_16x16x32_bf16 v[44:47], v[110:113], v[114:117], v[44:47]
	ds_read_b128 v[114:117], v102 offset:64
	v_mfma_f32_16x16x32_bf16 v[40:43], v[110:113], v[118:121], v[40:43]
	ds_read_b128 v[118:121], v103 offset:20800
	v_mfma_f32_16x16x32_bf16 v[92:95], v[110:113], v[122:125], v[92:95]
	ds_read_b128 v[122:125], v103 offset:23104
	v_mfma_f32_16x16x32_bf16 v[36:39], v[110:113], v[126:129], v[36:39]
	ds_read_b128 v[110:113], v103 offset:18496
	ds_read_b128 v[126:129], v103 offset:25408
	s_waitcnt lgkmcnt(1)
	v_mfma_f32_16x16x32_bf16 v[96:99], v[114:117], v[110:113], v[96:99]
	v_mfma_f32_16x16x32_bf16 v[88:91], v[114:117], v[118:121], v[88:91]
	v_mfma_f32_16x16x32_bf16 v[84:87], v[114:117], v[122:125], v[84:87]
	s_waitcnt lgkmcnt(0)
	v_mfma_f32_16x16x32_bf16 v[80:83], v[114:117], v[126:129], v[80:83]
	ds_read_b128 v[114:117], v102 offset:2368
	s_waitcnt lgkmcnt(0)
	v_mfma_f32_16x16x32_bf16 v[76:79], v[114:117], v[110:113], v[76:79]
	v_mfma_f32_16x16x32_bf16 v[130:133], v[114:117], v[118:121], v[72:75]
	v_mfma_f32_16x16x32_bf16 v[134:137], v[114:117], v[122:125], v[68:71]
	v_mfma_f32_16x16x32_bf16 v[64:67], v[114:117], v[126:129], v[64:67]
	s_nop 1
	ds_read_b128 v[68:71], v102 offset:4672
	ds_read_b128 v[114:117], v102 offset:6976
	s_waitcnt vmcnt(7)
	ds_write_b128 v107, v[4:7] offset:36864
	s_waitcnt vmcnt(6)
	ds_write_b128 v107, v[24:27] offset:41472
	s_waitcnt vmcnt(5)
	ds_write_b128 v107, v[8:11] offset:46080
	s_waitcnt vmcnt(4)
	ds_write_b128 v107, v[12:15] offset:50688
	s_waitcnt vmcnt(3)
	ds_write_b128 v107, v[28:31] offset:55296
	s_waitcnt vmcnt(2)
	ds_write_b128 v107, v[16:19] offset:59904
	s_waitcnt vmcnt(1)
	ds_write_b128 v107, v[20:23] offset:64512
	s_waitcnt vmcnt(0)
	ds_write_b128 v108, v[32:35] offset:32256
	s_waitcnt lgkmcnt(0)
	s_barrier
	ds_read_b128 v[16:19], v102 offset:36864
	ds_read_b128 v[20:23], v103 offset:55296
	ds_read_b128 v[28:31], v103 offset:57600
	ds_read_b128 v[12:15], v103 offset:59904
	ds_read_b128 v[8:11], v103 offset:62208
	v_mfma_f32_16x16x32_bf16 v[72:75], v[114:117], v[118:121], v[40:43]
	v_mfma_f32_16x16x32_bf16 v[4:7], v[114:117], v[126:129], v[36:39]
	s_waitcnt lgkmcnt(3)
	v_mfma_f32_16x16x32_bf16 v[24:27], v[16:19], v[20:23], v[96:99]
	s_waitcnt lgkmcnt(2)
	v_mfma_f32_16x16x32_bf16 v[32:35], v[16:19], v[28:31], v[88:91]
	s_waitcnt lgkmcnt(1)
	v_mfma_f32_16x16x32_bf16 v[36:39], v[16:19], v[12:15], v[84:87]
	s_waitcnt lgkmcnt(0)
	v_mfma_f32_16x16x32_bf16 v[40:43], v[16:19], v[8:11], v[80:83]
	ds_read_b128 v[16:19], v102 offset:39168
	v_mfma_f32_16x16x32_bf16 v[60:63], v[68:71], v[110:113], v[60:63]
	s_nop 0
	v_or_b32_e32 v80, s17, v101
	v_cmp_lt_i32_e32 vcc, s9, v80
	v_mfma_f32_16x16x32_bf16 v[56:59], v[68:71], v[118:121], v[56:59]
	v_mfma_f32_16x16x32_bf16 v[52:55], v[68:71], v[122:125], v[52:55]
	v_mfma_f32_16x16x32_bf16 v[48:51], v[68:71], v[126:129], v[48:51]
	v_mfma_f32_16x16x32_bf16 v[44:47], v[114:117], v[110:113], v[44:47]
	v_mfma_f32_16x16x32_bf16 v[68:71], v[114:117], v[122:125], v[92:95]
	s_waitcnt lgkmcnt(0)
	v_mfma_f32_16x16x32_bf16 v[88:91], v[16:19], v[20:23], v[76:79]
	v_mfma_f32_16x16x32_bf16 v[92:95], v[16:19], v[28:31], v[130:133]
	s_nop 1
	v_lshl_add_u32 v78, s8, 7, v106
	v_lshlrev_b32_e32 v76, 1, v100
	v_mfma_f32_16x16x32_bf16 v[96:99], v[16:19], v[12:15], v[134:137]
	v_mfma_f32_16x16x32_bf16 v[108:111], v[16:19], v[8:11], v[64:67]
	ds_read_b128 v[16:19], v102 offset:43776
	s_nop 1
	ds_read_b128 v[64:67], v102 offset:41472
	ds_read_b128 v[120:123], v102 offset:36928
	ds_read_b128 v[154:157], v103 offset:55360
	ds_read_b128 v[124:127], v102 offset:39232
	ds_read_b128 v[168:171], v103 offset:57664
	ds_read_b128 v[172:175], v102 offset:41536
	ds_read_b128 v[176:179], v103 offset:59968
	ds_read_b128 v[212:215], v102 offset:43840
	ds_read_b128 v[102:105], v103 offset:62272
	s_waitcnt lgkmcnt(8)
	v_mfma_f32_16x16x32_bf16 v[112:115], v[64:67], v[20:23], v[60:63]
	s_waitcnt lgkmcnt(0)
	s_barrier
; DI bf16_t f2bf(float f) { return (bf16_t)(pack2(f, f) & 0xFFFFu); }
; DI float sigmoidf_(float x) { return __builtin_amdgcn_rcpf(1.f + __expf(-x)); }
; DI void gemm_kloop(const bf16_t* __restrict__ A, int lda, const bf16_t* __restrict__ B, int ldb, int K, bf16_t* sm,
;                    f32x4 (&acc)[4][4]) {
;     ...
;   COMPUTE(0)
;   SSTORE(ra1, rb1, 1)
;   __syncthreads();
;   COMPUTE(1)
;   __syncthreads();
; DI void gemm2_phase(const Params& p, int l, char* smem, const bool dry = false) {
;     ...
;     } else {
; #pragma unroll
;       for (int i = 0; i < 4; i++)
; #pragma unroll
;         for (int r = 0; r < 4; r++) {
;           const int tok = mt * 128 + wm * 64 + i * 16 + g4 * 4 + r;
; #pragma unroll
;           for (int jn = 0; jn < 4; jn++)
;             p.G[(size_t)tok * 3072 + nb - 1536 + jn * 16 + cl] = f2bf(sigmoidf_(acc[i][jn][r]));
;         }
	v_mfma_f32_16x16x32_bf16 v[116:119], v[64:67], v[28:31], v[56:59]
	v_mfma_f32_16x16x32_bf16 v[158:161], v[64:67], v[12:15], v[52:55]
	v_mfma_f32_16x16x32_bf16 v[208:211], v[64:67], v[8:11], v[48:51]
	v_mfma_f32_16x16x32_bf16 v[216:219], v[16:19], v[20:23], v[44:47]
	v_mfma_f32_16x16x32_bf16 v[72:75], v[16:19], v[28:31], v[72:75]
	v_mfma_f32_16x16x32_bf16 v[68:71], v[16:19], v[12:15], v[68:71]
	v_mfma_f32_16x16x32_bf16 v[4:7], v[16:19], v[8:11], v[4:7]
	v_mfma_f32_16x16x32_bf16 v[64:67], v[120:123], v[154:157], v[24:27]
	v_mfma_f32_16x16x32_bf16 v[60:63], v[120:123], v[168:171], v[32:35]
	v_mfma_f32_16x16x32_bf16 v[56:59], v[120:123], v[176:179], v[36:39]
	s_nop 5
	v_mul_f32_e32 v86, 0xbfb8aa3b, v64
	v_mul_f32_e32 v85, 0xbfb8aa3b, v60
	v_mul_f32_e32 v82, 0xbfb8aa3b, v65
	v_mfma_f32_16x16x32_bf16 v[52:55], v[120:123], v[102:105], v[40:43]
	v_mul_f32_e32 v153, 0xbfb8aa3b, v61
	v_mul_f32_e32 v84, 0xbfb8aa3b, v56
	v_mul_f32_e32 v152, 0xbfb8aa3b, v57
	v_mfma_f32_16x16x32_bf16 v[48:51], v[124:127], v[154:157], v[88:91]
	v_mul_f32_e32 v150, 0xbfb8aa3b, v66
	s_nop 2
	v_mul_f32_e32 v83, 0xbfb8aa3b, v52
	v_mul_f32_e32 v151, 0xbfb8aa3b, v53
	v_mfma_f32_16x16x32_bf16 v[44:47], v[124:127], v[168:171], v[92:95]
	v_mul_f32_e32 v149, 0xbfb8aa3b, v62
	v_mul_f32_e32 v148, 0xbfb8aa3b, v58
	v_mul_f32_e32 v147, 0xbfb8aa3b, v54
	v_mfma_f32_16x16x32_bf16 v[40:43], v[124:127], v[176:179], v[96:99]
	v_mul_f32_e32 v146, 0xbfb8aa3b, v67
	v_mul_f32_e32 v145, 0xbfb8aa3b, v63
	v_mul_f32_e32 v144, 0xbfb8aa3b, v59
	v_mfma_f32_16x16x32_bf16 v[36:39], v[124:127], v[102:105], v[108:111]
	v_mul_f32_e32 v143, 0xbfb8aa3b, v55
	v_mul_f32_e32 v142, 0xbfb8aa3b, v48
	v_mul_f32_e32 v141, 0xbfb8aa3b, v44
	v_mfma_f32_16x16x32_bf16 v[32:35], v[172:175], v[154:157], v[112:115]
	v_mul_f32_e32 v140, 0xbfb8aa3b, v40
	s_nop 2
	v_mul_f32_e32 v139, 0xbfb8aa3b, v36
	v_mul_f32_e32 v138, 0xbfb8aa3b, v49
	v_mfma_f32_16x16x32_bf16 v[28:31], v[172:175], v[168:171], v[116:119]
	v_mul_f32_e32 v137, 0xbfb8aa3b, v45
	v_mul_f32_e32 v136, 0xbfb8aa3b, v41
	v_mul_f32_e32 v135, 0xbfb8aa3b, v37
	v_mfma_f32_16x16x32_bf16 v[24:27], v[172:175], v[176:179], v[158:161]
	v_mul_f32_e32 v134, 0xbfb8aa3b, v50
	v_mul_f32_e32 v133, 0xbfb8aa3b, v46
	v_mul_f32_e32 v132, 0xbfb8aa3b, v42
	v_mfma_f32_16x16x32_bf16 v[20:23], v[172:175], v[102:105], v[208:211]
	v_mul_f32_e32 v131, 0xbfb8aa3b, v38
	v_mul_f32_e32 v130, 0xbfb8aa3b, v51
	v_mul_f32_e32 v129, 0xbfb8aa3b, v47
	v_mfma_f32_16x16x32_bf16 v[16:19], v[212:215], v[154:157], v[216:219]
	v_mul_f32_e32 v128, 0xbfb8aa3b, v43
	v_mul_f32_e32 v127, 0xbfb8aa3b, v39
	v_mul_f32_e32 v126, 0xbfb8aa3b, v32
	v_mfma_f32_16x16x32_bf16 v[12:15], v[212:215], v[168:171], v[72:75]
	v_mul_f32_e32 v125, 0xbfb8aa3b, v28
	v_mul_f32_e32 v124, 0xbfb8aa3b, v24
	v_mul_f32_e32 v123, 0xbfb8aa3b, v20
	v_mfma_f32_16x16x32_bf16 v[8:11], v[212:215], v[176:179], v[68:71]
	v_mul_f32_e32 v122, 0xbfb8aa3b, v33
	v_mul_f32_e32 v121, 0xbfb8aa3b, v29
	v_mul_f32_e32 v120, 0xbfb8aa3b, v25
	v_mfma_f32_16x16x32_bf16 v[4:7], v[212:215], v[102:105], v[4:7]
	v_mul_f32_e32 v119, 0xbfb8aa3b, v21
	v_mul_f32_e32 v118, 0xbfb8aa3b, v34
	v_mul_f32_e32 v117, 0xbfb8aa3b, v30
	v_mul_f32_e32 v116, 0xbfb8aa3b, v26
	v_mul_f32_e32 v115, 0xbfb8aa3b, v22
	v_mul_f32_e32 v114, 0xbfb8aa3b, v35
	v_mul_f32_e32 v113, 0xbfb8aa3b, v31
	v_mul_f32_e32 v112, 0xbfb8aa3b, v27
	v_mul_f32_e32 v111, 0xbfb8aa3b, v23
	v_mul_f32_e32 v110, 0xbfb8aa3b, v16
	v_mul_f32_e32 v109, 0xbfb8aa3b, v12
	v_mul_f32_e32 v108, 0xbfb8aa3b, v8
	v_mul_f32_e32 v107, 0xbfb8aa3b, v4
	v_mul_f32_e32 v105, 0xbfb8aa3b, v17
	v_mul_f32_e32 v104, 0xbfb8aa3b, v13
	v_mul_f32_e32 v103, 0xbfb8aa3b, v9
	v_mul_f32_e32 v102, 0xbfb8aa3b, v5
	v_mul_f32_e32 v99, 0xbfb8aa3b, v18
	v_mul_f32_e32 v98, 0xbfb8aa3b, v14
	v_mul_f32_e32 v97, 0xbfb8aa3b, v10
	v_mul_f32_e32 v96, 0xbfb8aa3b, v6
	v_mul_f32_e32 v95, 0xbfb8aa3b, v19
	v_mul_f32_e32 v94, 0xbfb8aa3b, v15
	v_mul_f32_e32 v93, 0xbfb8aa3b, v11
	v_mul_f32_e32 v92, 0xbfb8aa3b, v7
	s_and_saveexec_b64 s[8:9], vcc
	s_xor_b64 s[8:9], exec, s[8:9]
	s_cbranch_execz .LBB0_1704
	v_exp_f32_e32 v8, v86
	v_exp_f32_e32 v9, v85
	s_load_dwordx2 s[10:11], s[0:1], 0x160
	v_mov_b32_e32 v81, v164
	v_add_f32_e32 v8, 1.0, v8
	v_rcp_f32_e32 v8, v8
	v_add_f32_e32 v9, 1.0, v9
	v_rcp_f32_e32 v9, v9
	v_exp_f32_e32 v10, v84
	s_waitcnt lgkmcnt(0)
; DI bf16_t f2bf(float f) { return (bf16_t)(pack2(f, f) & 0xFFFFu); }
; DI float sigmoidf_(float x) { return __builtin_amdgcn_rcpf(1.f + __expf(-x)); }
; DI void gemm2_phase(const Params& p, int l, char* smem, const bool dry = false) {
;     ...
; #pragma unroll
;       for (int i = 0; i < 4; i++)
; #pragma unroll
;         for (int r = 0; r < 4; r++) {
;           const int tok = mt * 128 + wm * 64 + i * 16 + g4 * 4 + r;
; #pragma unroll
;           for (int jn = 0; jn < 4; jn++)
;             p.G[(size_t)tok * 3072 + nb - 1536 + jn * 16 + cl] = f2bf(sigmoidf_(acc[i][jn][r]));
;         }
	v_lshl_add_u64 v[4:5], v[80:81], 1, s[10:11]
	s_movk_i32 s12, 0x1800
	v_mov_b32_e32 v77, v164
	v_mad_i64_i32 v[6:7], s[10:11], v78, s12, v[4:5]
	v_lshl_add_u64 v[6:7], v[6:7], 0, v[76:77]
	v_cvt_pk_bf16_f32 v8, v8, s0
	global_store_short v[6:7], v8, off offset:-3072
	v_cvt_pk_bf16_f32 v8, v9, s0
	v_exp_f32_e32 v9, v83
	v_add_f32_e32 v10, 1.0, v10
	v_rcp_f32_e32 v10, v10
	global_store_short v[6:7], v8, off offset:-3040
	v_add_f32_e32 v8, 1.0, v9
	v_rcp_f32_e32 v8, v8
	v_cvt_pk_bf16_f32 v9, v10, s0
	global_store_short v[6:7], v9, off offset:-3008
	v_exp_f32_e32 v9, v82
	v_cvt_pk_bf16_f32 v8, v8, s0
	global_store_short v[6:7], v8, off offset:-2976
	v_or_b32_e32 v6, 1, v78
	v_add_f32_e32 v7, 1.0, v9
	v_rcp_f32_e32 v8, v7
	v_mad_i64_i32 v[6:7], s[10:11], v6, s12, v[4:5]
	v_lshl_add_u64 v[6:7], v[6:7], 0, v[76:77]
	v_cvt_pk_bf16_f32 v8, v8, s0
	v_exp_f32_e32 v9, v153
	global_store_short v[6:7], v8, off offset:-3072
	v_exp_f32_e32 v8, v151
	v_exp_f32_e32 v10, v152
	v_add_f32_e32 v9, 1.0, v9
	v_rcp_f32_e32 v9, v9
	v_add_f32_e32 v8, 1.0, v8
	v_add_f32_e32 v10, 1.0, v10
	v_rcp_f32_e32 v8, v8
	v_rcp_f32_e32 v10, v10
	v_cvt_pk_bf16_f32 v9, v9, s0
	global_store_short v[6:7], v9, off offset:-3040
	v_cvt_pk_bf16_f32 v8, v8, s0
	v_cvt_pk_bf16_f32 v9, v10, s0
	global_store_short v[6:7], v8, off offset:-2976
	v_exp_f32_e32 v8, v150
	global_store_short v[6:7], v9, off offset:-3008
	v_exp_f32_e32 v9, v149
	v_exp_f32_e32 v10, v148
	v_add_f32_e32 v8, 1.0, v8
	v_rcp_f32_e32 v8, v8
	v_add_f32_e32 v9, 1.0, v9
	v_rcp_f32_e32 v9, v9
	v_or_b32_e32 v6, 2, v78
	v_mad_i64_i32 v[6:7], s[10:11], v6, s12, v[4:5]
	v_lshl_add_u64 v[6:7], v[6:7], 0, v[76:77]
	v_cvt_pk_bf16_f32 v8, v8, s0
	global_store_short v[6:7], v8, off offset:-3072
	v_cvt_pk_bf16_f32 v8, v9, s0
	v_exp_f32_e32 v9, v147
	v_add_f32_e32 v10, 1.0, v10
	v_rcp_f32_e32 v10, v10
	global_store_short v[6:7], v8, off offset:-3040
	v_add_f32_e32 v8, 1.0, v9
	v_rcp_f32_e32 v8, v8
	v_cvt_pk_bf16_f32 v9, v10, s0
	global_store_short v[6:7], v9, off offset:-3008
	v_exp_f32_e32 v9, v146
	v_cvt_pk_bf16_f32 v8, v8, s0
	global_store_short v[6:7], v8, off offset:-2976
	v_or_b32_e32 v6, 3, v78
	v_add_f32_e32 v7, 1.0, v9
	v_rcp_f32_e32 v8, v7
	v_mad_i64_i32 v[6:7], s[10:11], v6, s12, v[4:5]
	v_lshl_add_u64 v[6:7], v[6:7], 0, v[76:77]
	v_cvt_pk_bf16_f32 v8, v8, s0
	v_exp_f32_e32 v9, v145
	global_store_short v[6:7], v8, off offset:-3072
	v_exp_f32_e32 v8, v143
	v_exp_f32_e32 v10, v144
	v_add_f32_e32 v9, 1.0, v9
	v_rcp_f32_e32 v9, v9
	v_add_f32_e32 v8, 1.0, v8
	v_add_f32_e32 v10, 1.0, v10
	v_rcp_f32_e32 v8, v8
	v_rcp_f32_e32 v10, v10
	v_cvt_pk_bf16_f32 v9, v9, s0
	global_store_short v[6:7], v9, off offset:-3040
	v_cvt_pk_bf16_f32 v8, v8, s0
	v_cvt_pk_bf16_f32 v9, v10, s0
	global_store_short v[6:7], v8, off offset:-2976
	v_exp_f32_e32 v8, v142
	global_store_short v[6:7], v9, off offset:-3008
	v_exp_f32_e32 v9, v141
	v_exp_f32_e32 v10, v140
	v_add_f32_e32 v8, 1.0, v8
	v_rcp_f32_e32 v8, v8
	v_add_f32_e32 v9, 1.0, v9
	v_rcp_f32_e32 v9, v9
	v_or_b32_e32 v6, 16, v78
	v_mad_i64_i32 v[6:7], s[10:11], v6, s12, v[4:5]
	v_lshl_add_u64 v[6:7], v[6:7], 0, v[76:77]
	v_cvt_pk_bf16_f32 v8, v8, s0
	global_store_short v[6:7], v8, off offset:-3072
	v_cvt_pk_bf16_f32 v8, v9, s0
	v_exp_f32_e32 v9, v139
	v_add_f32_e32 v10, 1.0, v10
	v_rcp_f32_e32 v10, v10
	global_store_short v[6:7], v8, off offset:-3040
	v_add_f32_e32 v8, 1.0, v9
	v_rcp_f32_e32 v8, v8
	v_cvt_pk_bf16_f32 v9, v10, s0
	global_store_short v[6:7], v9, off offset:-3008
	v_exp_f32_e32 v9, v138
	v_cvt_pk_bf16_f32 v8, v8, s0
	global_store_short v[6:7], v8, off offset:-2976
	v_or_b32_e32 v6, 17, v78
	v_add_f32_e32 v7, 1.0, v9
	v_rcp_f32_e32 v8, v7
	v_mad_i64_i32 v[6:7], s[10:11], v6, s12, v[4:5]
	v_lshl_add_u64 v[6:7], v[6:7], 0, v[76:77]
	v_cvt_pk_bf16_f32 v8, v8, s0
	v_exp_f32_e32 v9, v137
	global_store_short v[6:7], v8, off offset:-3072
	v_exp_f32_e32 v8, v135
	v_exp_f32_e32 v10, v136
	v_add_f32_e32 v9, 1.0, v9
	v_rcp_f32_e32 v9, v9
	v_add_f32_e32 v8, 1.0, v8
	v_add_f32_e32 v10, 1.0, v10
	v_rcp_f32_e32 v8, v8
	v_rcp_f32_e32 v10, v10
	v_cvt_pk_bf16_f32 v9, v9, s0
	global_store_short v[6:7], v9, off offset:-3040
	v_cvt_pk_bf16_f32 v8, v8, s0
	v_cvt_pk_bf16_f32 v9, v10, s0
	global_store_short v[6:7], v8, off offset:-2976
	v_exp_f32_e32 v8, v134
	global_store_short v[6:7], v9, off offset:-3008
	v_exp_f32_e32 v9, v133
	v_exp_f32_e32 v10, v132
	v_add_f32_e32 v8, 1.0, v8
	v_rcp_f32_e32 v8, v8
	v_add_f32_e32 v9, 1.0, v9
	v_rcp_f32_e32 v9, v9
	v_or_b32_e32 v6, 18, v78
	v_mad_i64_i32 v[6:7], s[10:11], v6, s12, v[4:5]
	v_lshl_add_u64 v[6:7], v[6:7], 0, v[76:77]
	v_cvt_pk_bf16_f32 v8, v8, s0
	global_store_short v[6:7], v8, off offset:-3072
	v_cvt_pk_bf16_f32 v8, v9, s0
	v_exp_f32_e32 v9, v131
	v_add_f32_e32 v10, 1.0, v10
	v_rcp_f32_e32 v10, v10
	global_store_short v[6:7], v8, off offset:-3040
	v_add_f32_e32 v8, 1.0, v9
	v_rcp_f32_e32 v8, v8
	v_cvt_pk_bf16_f32 v9, v10, s0
	global_store_short v[6:7], v9, off offset:-3008
	v_exp_f32_e32 v9, v130
	v_cvt_pk_bf16_f32 v8, v8, s0
	global_store_short v[6:7], v8, off offset:-2976
	v_or_b32_e32 v6, 19, v78
	v_add_f32_e32 v7, 1.0, v9
	v_rcp_f32_e32 v8, v7
	v_mad_i64_i32 v[6:7], s[10:11], v6, s12, v[4:5]
	v_lshl_add_u64 v[6:7], v[6:7], 0, v[76:77]
	v_cvt_pk_bf16_f32 v8, v8, s0
	v_exp_f32_e32 v9, v129
	global_store_short v[6:7], v8, off offset:-3072
	v_exp_f32_e32 v8, v127
	v_exp_f32_e32 v10, v128
	v_add_f32_e32 v9, 1.0, v9
	v_rcp_f32_e32 v9, v9
	v_add_f32_e32 v8, 1.0, v8
	v_add_f32_e32 v10, 1.0, v10
	v_rcp_f32_e32 v8, v8
	v_rcp_f32_e32 v10, v10
	v_cvt_pk_bf16_f32 v9, v9, s0
	global_store_short v[6:7], v9, off offset:-3040
	v_cvt_pk_bf16_f32 v8, v8, s0
; DI bf16_t f2bf(float f) { return (bf16_t)(pack2(f, f) & 0xFFFFu); }
; DI float sigmoidf_(float x) { return __builtin_amdgcn_rcpf(1.f + __expf(-x)); }
; DI void gemm2_phase(const Params& p, int l, char* smem, const bool dry = false) {
;     ...
; #pragma unroll
;       for (int i = 0; i < 4; i++)
; #pragma unroll
;         for (int r = 0; r < 4; r++) {
;           const int tok = mt * 128 + wm * 64 + i * 16 + g4 * 4 + r;
; #pragma unroll
;           for (int jn = 0; jn < 4; jn++)
;             p.G[(size_t)tok * 3072 + nb - 1536 + jn * 16 + cl] = f2bf(sigmoidf_(acc[i][jn][r]));
;         }
	v_cvt_pk_bf16_f32 v9, v10, s0
	global_store_short v[6:7], v8, off offset:-2976
	v_exp_f32_e32 v8, v126
	global_store_short v[6:7], v9, off offset:-3008
	v_exp_f32_e32 v9, v125
	v_exp_f32_e32 v10, v124
	v_add_f32_e32 v8, 1.0, v8
	v_rcp_f32_e32 v8, v8
	v_add_f32_e32 v9, 1.0, v9
	v_rcp_f32_e32 v9, v9
	v_or_b32_e32 v6, 32, v78
	v_mad_i64_i32 v[6:7], s[10:11], v6, s12, v[4:5]
	v_lshl_add_u64 v[6:7], v[6:7], 0, v[76:77]
	v_cvt_pk_bf16_f32 v8, v8, s0
	global_store_short v[6:7], v8, off offset:-3072
	v_cvt_pk_bf16_f32 v8, v9, s0
	v_exp_f32_e32 v9, v123
	v_add_f32_e32 v10, 1.0, v10
	v_rcp_f32_e32 v10, v10
	global_store_short v[6:7], v8, off offset:-3040
	v_add_f32_e32 v8, 1.0, v9
	v_rcp_f32_e32 v8, v8
	v_cvt_pk_bf16_f32 v9, v10, s0
	global_store_short v[6:7], v9, off offset:-3008
	v_exp_f32_e32 v9, v122
	v_cvt_pk_bf16_f32 v8, v8, s0
	global_store_short v[6:7], v8, off offset:-2976
	v_or_b32_e32 v6, 33, v78
	v_add_f32_e32 v7, 1.0, v9
	v_rcp_f32_e32 v8, v7
	v_mad_i64_i32 v[6:7], s[10:11], v6, s12, v[4:5]
	v_lshl_add_u64 v[6:7], v[6:7], 0, v[76:77]
	v_cvt_pk_bf16_f32 v8, v8, s0
	v_exp_f32_e32 v9, v121
	global_store_short v[6:7], v8, off offset:-3072
	v_exp_f32_e32 v8, v119
	v_exp_f32_e32 v10, v120
	v_add_f32_e32 v9, 1.0, v9
	v_rcp_f32_e32 v9, v9
	v_add_f32_e32 v8, 1.0, v8
	v_add_f32_e32 v10, 1.0, v10
	v_rcp_f32_e32 v8, v8
	v_rcp_f32_e32 v10, v10
	v_cvt_pk_bf16_f32 v9, v9, s0
	global_store_short v[6:7], v9, off offset:-3040
	v_cvt_pk_bf16_f32 v8, v8, s0
	v_cvt_pk_bf16_f32 v9, v10, s0
	global_store_short v[6:7], v8, off offset:-2976
	v_exp_f32_e32 v8, v118
	global_store_short v[6:7], v9, off offset:-3008
	v_exp_f32_e32 v9, v117
	v_exp_f32_e32 v10, v116
	v_add_f32_e32 v8, 1.0, v8
	v_rcp_f32_e32 v8, v8
	v_add_f32_e32 v9, 1.0, v9
	v_rcp_f32_e32 v9, v9
	v_or_b32_e32 v6, 34, v78
	v_mad_i64_i32 v[6:7], s[10:11], v6, s12, v[4:5]
	v_lshl_add_u64 v[6:7], v[6:7], 0, v[76:77]
	v_cvt_pk_bf16_f32 v8, v8, s0
	global_store_short v[6:7], v8, off offset:-3072
	v_cvt_pk_bf16_f32 v8, v9, s0
	v_exp_f32_e32 v9, v115
	v_add_f32_e32 v10, 1.0, v10
	v_rcp_f32_e32 v10, v10
	global_store_short v[6:7], v8, off offset:-3040
	v_add_f32_e32 v8, 1.0, v9
	v_rcp_f32_e32 v8, v8
	v_cvt_pk_bf16_f32 v9, v10, s0
	global_store_short v[6:7], v9, off offset:-3008
	v_exp_f32_e32 v9, v114
	v_cvt_pk_bf16_f32 v8, v8, s0
	global_store_short v[6:7], v8, off offset:-2976
	v_or_b32_e32 v6, 35, v78
	v_add_f32_e32 v7, 1.0, v9
	v_rcp_f32_e32 v8, v7
	v_mad_i64_i32 v[6:7], s[10:11], v6, s12, v[4:5]
	v_lshl_add_u64 v[6:7], v[6:7], 0, v[76:77]
	v_cvt_pk_bf16_f32 v8, v8, s0
	v_exp_f32_e32 v9, v113
	global_store_short v[6:7], v8, off offset:-3072
	v_exp_f32_e32 v8, v111
	v_exp_f32_e32 v10, v112
	v_add_f32_e32 v9, 1.0, v9
	v_rcp_f32_e32 v9, v9
	v_add_f32_e32 v8, 1.0, v8
	v_add_f32_e32 v10, 1.0, v10
	v_rcp_f32_e32 v8, v8
	v_rcp_f32_e32 v10, v10
	v_cvt_pk_bf16_f32 v9, v9, s0
	global_store_short v[6:7], v9, off offset:-3040
	v_cvt_pk_bf16_f32 v8, v8, s0
	v_cvt_pk_bf16_f32 v9, v10, s0
	global_store_short v[6:7], v8, off offset:-2976
	v_exp_f32_e32 v8, v110
	global_store_short v[6:7], v9, off offset:-3008
	v_exp_f32_e32 v9, v109
	v_exp_f32_e32 v10, v108
	v_add_f32_e32 v8, 1.0, v8
	v_rcp_f32_e32 v8, v8
	v_add_f32_e32 v9, 1.0, v9
	v_rcp_f32_e32 v9, v9
	v_or_b32_e32 v6, 48, v78
	v_mad_i64_i32 v[6:7], s[10:11], v6, s12, v[4:5]
	v_lshl_add_u64 v[6:7], v[6:7], 0, v[76:77]
	v_cvt_pk_bf16_f32 v8, v8, s0
	global_store_short v[6:7], v8, off offset:-3072
	v_cvt_pk_bf16_f32 v8, v9, s0
	v_exp_f32_e32 v9, v107
	v_add_f32_e32 v10, 1.0, v10
	v_rcp_f32_e32 v10, v10
	global_store_short v[6:7], v8, off offset:-3040
	v_add_f32_e32 v8, 1.0, v9
	v_rcp_f32_e32 v8, v8
	v_cvt_pk_bf16_f32 v9, v10, s0
	global_store_short v[6:7], v9, off offset:-3008
	v_exp_f32_e32 v9, v105
	v_cvt_pk_bf16_f32 v8, v8, s0
	global_store_short v[6:7], v8, off offset:-2976
	v_or_b32_e32 v6, 49, v78
	v_add_f32_e32 v7, 1.0, v9
	v_rcp_f32_e32 v8, v7
	v_mad_i64_i32 v[6:7], s[10:11], v6, s12, v[4:5]
	v_lshl_add_u64 v[6:7], v[6:7], 0, v[76:77]
	v_cvt_pk_bf16_f32 v8, v8, s0
	v_exp_f32_e32 v9, v104
	global_store_short v[6:7], v8, off offset:-3072
	v_exp_f32_e32 v8, v102
	v_exp_f32_e32 v10, v103
	v_add_f32_e32 v9, 1.0, v9
	v_rcp_f32_e32 v9, v9
	v_add_f32_e32 v8, 1.0, v8
	v_add_f32_e32 v10, 1.0, v10
	v_rcp_f32_e32 v8, v8
	v_rcp_f32_e32 v10, v10
	v_cvt_pk_bf16_f32 v9, v9, s0
	global_store_short v[6:7], v9, off offset:-3040
	v_cvt_pk_bf16_f32 v8, v8, s0
	v_cvt_pk_bf16_f32 v9, v10, s0
	global_store_short v[6:7], v8, off offset:-2976
	v_exp_f32_e32 v8, v99
	global_store_short v[6:7], v9, off offset:-3008
	v_exp_f32_e32 v9, v98
	v_exp_f32_e32 v10, v97
	v_add_f32_e32 v8, 1.0, v8
	v_rcp_f32_e32 v8, v8
	v_add_f32_e32 v9, 1.0, v9
	v_rcp_f32_e32 v9, v9
	v_or_b32_e32 v6, 50, v78
	v_mad_i64_i32 v[6:7], s[10:11], v6, s12, v[4:5]
	v_lshl_add_u64 v[6:7], v[6:7], 0, v[76:77]
	v_cvt_pk_bf16_f32 v8, v8, s0
	global_store_short v[6:7], v8, off offset:-3072
	v_cvt_pk_bf16_f32 v8, v9, s0
	v_exp_f32_e32 v9, v96
	v_add_f32_e32 v10, 1.0, v10
	v_rcp_f32_e32 v10, v10
	global_store_short v[6:7], v8, off offset:-3040
	v_add_f32_e32 v8, 1.0, v9
	v_rcp_f32_e32 v8, v8
	v_cvt_pk_bf16_f32 v9, v10, s0
	global_store_short v[6:7], v9, off offset:-3008
	v_exp_f32_e32 v9, v95
	v_cvt_pk_bf16_f32 v8, v8, s0
	global_store_short v[6:7], v8, off offset:-2976
	v_exp_f32_e32 v8, v94
	v_add_f32_e32 v7, 1.0, v9
	v_rcp_f32_e32 v7, v7
	v_or_b32_e32 v6, 51, v78
	v_mad_i64_i32 v[4:5], s[10:11], v6, s12, v[4:5]
	v_lshl_add_u64 v[4:5], v[4:5], 0, v[76:77]
	v_cvt_pk_bf16_f32 v6, v7, s0
	v_add_f32_e32 v7, 1.0, v8
	v_exp_f32_e32 v8, v93
	global_store_short v[4:5], v6, off offset:-3072
	v_exp_f32_e32 v6, v92
	v_rcp_f32_e32 v7, v7
	v_add_f32_e32 v8, 1.0, v8
	v_rcp_f32_e32 v8, v8
	v_add_f32_e32 v6, 1.0, v6
	v_rcp_f32_e32 v6, v6
	v_cvt_pk_bf16_f32 v7, v7, s0
	global_store_short v[4:5], v7, off offset:-3040
	v_cvt_pk_bf16_f32 v7, v8, s0
	v_cvt_pk_bf16_f32 v6, v6, s0
	global_store_short v[4:5], v7, off offset:-3008
	global_store_short v[4:5], v6, off offset:-2976
